# v24: nontemporal hint on the 32 residual (x) loads of the GEMM3b epilogue (streamed once, keeps A/B tiles in L2)
# baseline (speedup 1.0000x reference)
;     __device__ __forceinline__ void operator()(f32x4 (&acc)[2][2][4][2], const pg8::Unit& u, int wr, int wc, int fr, int fq, LAS unsigned char* lds, int wid, int lane) const {
;     ...
;         for (int ai = 0; ai < 2; ++ai) {
;             f32x4 xv[4][2][2];
; #pragma unroll
;             for (int m = 0; m < 4; ++m) { const char* xp = (const char*)x + (size_t)(boff + (unsigned)((ai * 128 + m * 16) * DM * 4));
; #pragma unroll
;                 for (int bj = 0; bj < 2; ++bj)
; #pragma unroll
;                     for (int n = 0; n < 2; ++n) xv[m][bj][n] = *(const f32x4*)(xp + (bj * 128 + n * 16) * 4); }
;             __builtin_amdgcn_sched_barrier(0);
; #pragma unroll
;             for (int m = 0; m < 4; ++m) { float ss = 0.f;
; #pragma unroll
;                 for (int bj = 0; bj < 2; ++bj)
; #pragma unroll
;                     for (int n = 0; n < 2; ++n) { const f32x4 y = acc[ai][bj][m][n] + xv[m][bj][n]; acc[ai][bj][m][n] = y; ss += (y[0] * y[0] + y[1] * y[1]) + (y[2] * y[2] + y[3] * y[3]); }
;                 ss += __shfl_xor(ss, 16); ss += __shfl_xor(ss, 32);
;                 if (fq == 0) Pt[(ai * 128 + wr * 64 + m * 16 + fr) * 4 + wc] = ss; }
.LBB0_869:
	s_lshl_b32 s11, s10, 8
	v_lshl_or_b32 v200, s30, 8, v208
	v_add_u32_e32 v128, s11, v206
	v_lshlrev_b32_e32 v129, 2, v200
	v_lshl_add_u32 v180, v128, 12, v129
	global_load_dwordx4 v[194:197], v180, s[40:41] nt
	global_load_dwordx4 v[202:205], v180, s[40:41] offset:64 nt
	global_load_dwordx4 v[220:223], v180, s[40:41] offset:512 nt
	global_load_dwordx4 v[224:227], v180, s[40:41] offset:576 nt
	v_add_u32_e32 v198, 0x10000, v180
	v_add_u32_e32 v192, 0x20000, v180
	v_add_u32_e32 v190, 0x30000, v180
	global_load_dwordx4 v[172:175], v198, s[40:41] nt
	global_load_dwordx4 v[168:171], v198, s[40:41] offset:64 nt
	global_load_dwordx4 v[164:167], v198, s[40:41] offset:512 nt
	global_load_dwordx4 v[160:163], v198, s[40:41] offset:576 nt
	global_load_dwordx4 v[156:159], v192, s[40:41] nt
	global_load_dwordx4 v[152:155], v192, s[40:41] offset:64 nt
	global_load_dwordx4 v[148:151], v192, s[40:41] offset:512 nt
	global_load_dwordx4 v[144:147], v192, s[40:41] offset:576 nt
	global_load_dwordx4 v[140:143], v190, s[40:41] nt
	global_load_dwordx4 v[136:139], v190, s[40:41] offset:64 nt
	global_load_dwordx4 v[132:135], v190, s[40:41] offset:512 nt
	global_load_dwordx4 v[128:131], v190, s[40:41] offset:576 nt
	v_and_b32_e32 v193, 64, v215
	v_xor_b32_e32 v191, 16, v215
	v_add_u32_e32 v193, 64, v193
	v_cmp_lt_i32_e32 vcc, v191, v193
	v_xor_b32_e32 v199, 32, v215
	s_nop 0
	v_cndmask_b32_e32 v191, v215, v191, vcc
	v_cmp_lt_i32_e32 vcc, v199, v193
	v_lshlrev_b32_e32 v191, 2, v191
	s_nop 0
	v_cndmask_b32_e32 v193, v215, v199, vcc
	v_lshlrev_b32_e32 v193, 2, v193
	s_waitcnt vmcnt(0)
	v_pk_add_f32 v[126:127], v[126:127], v[196:197]
	v_pk_add_f32 v[124:125], v[124:125], v[194:195]
	v_mul_f32_e32 v195, v127, v127
	v_mul_f32_e32 v194, v125, v125
	v_fmac_f32_e32 v194, v124, v124
	v_fmac_f32_e32 v195, v126, v126
	v_pk_add_f32 v[122:123], v[122:123], v[204:205]
	v_pk_add_f32 v[120:121], v[120:121], v[202:203]
	v_add_f32_e32 v194, v194, v195
	v_mul_f32_e32 v195, v121, v121
	v_mul_f32_e32 v196, v123, v123
	v_fmac_f32_e32 v195, v120, v120
	v_fmac_f32_e32 v196, v122, v122
	v_add_f32_e32 v195, v195, v196
	v_pk_add_f32 v[118:119], v[118:119], v[222:223]
	v_pk_add_f32 v[116:117], v[116:117], v[220:221]
	v_add_f32_e32 v194, v194, v195
	v_mul_f32_e32 v195, v117, v117
	v_mul_f32_e32 v196, v119, v119
	v_fmac_f32_e32 v195, v116, v116
	v_fmac_f32_e32 v196, v118, v118
	v_add_f32_e32 v195, v195, v196
	v_add_f32_e32 v199, v194, v195
	v_pk_add_f32 v[194:195], v[110:111], v[226:227]
	v_pk_add_f32 v[196:197], v[108:109], v[224:225]
	v_mul_f32_e32 v109, v195, v195
	v_mul_f32_e32 v108, v197, v197
	v_fmac_f32_e32 v108, v196, v196
	v_fmac_f32_e32 v109, v194, v194
	v_add_f32_e32 v108, v108, v109
	v_add_f32_e32 v108, v199, v108
	ds_bpermute_b32 v109, v191, v108
	s_waitcnt lgkmcnt(0)
	v_add_f32_e32 v108, v108, v109
	ds_bpermute_b32 v109, v193, v108
	s_and_saveexec_b64 s[34:35], s[0:1]
	s_cbranch_execz .LBB0_871
	s_waitcnt lgkmcnt(0)
	v_add_f32_e32 v108, v108, v109
	ds_write_b32 v219, v108

;     __device__ __forceinline__ void operator()(f32x4 (&acc)[2][2][4][2], const pg8::Unit& u, int wr, int wc, int fr, int fq, LAS unsigned char* lds, int wid, int lane) const {
;     ...
;         for (int ai = 0; ai < 2; ++ai) {
;             f32x4 xv[4][2][2];
; #pragma unroll
;             for (int m = 0; m < 4; ++m) { const char* xp = (const char*)x + (size_t)(boff + (unsigned)((ai * 128 + m * 16) * DM * 4));
; #pragma unroll
;                 for (int bj = 0; bj < 2; ++bj)
; #pragma unroll
;                     for (int n = 0; n < 2; ++n) xv[m][bj][n] = *(const f32x4*)(xp + (bj * 128 + n * 16) * 4); }
;             __builtin_amdgcn_sched_barrier(0);
; #pragma unroll
;             for (int m = 0; m < 4; ++m) { float ss = 0.f;
; #pragma unroll
;                 for (int bj = 0; bj < 2; ++bj)
; #pragma unroll
;                     for (int n = 0; n < 2; ++n) { const f32x4 y = acc[ai][bj][m][n] + xv[m][bj][n]; acc[ai][bj][m][n] = y; ss += (y[0] * y[0] + y[1] * y[1]) + (y[2] * y[2] + y[3] * y[3]); }
;                 ss += __shfl_xor(ss, 16); ss += __shfl_xor(ss, 32);
;                 if (fq == 0) Pt[(ai * 128 + wr * 64 + m * 16 + fr) * 4 + wc] = ss; }
.LBB0_877:
	s_or_b64 exec, exec, s[34:35]
	v_add_u32_e32 v174, 0x80000, v180
	v_add_u32_e32 v130, 0x90000, v180
	v_add_u32_e32 v128, 0xa0000, v180
	v_add_u32_e32 v112, 0xb0000, v180
	global_load_dwordx4 v[220:223], v174, s[40:41] nt
	global_load_dwordx4 v[224:227], v174, s[40:41] offset:64 nt
	global_load_dwordx4 v[228:231], v174, s[40:41] offset:512 nt
	global_load_dwordx4 v[232:235], v174, s[40:41] offset:576 nt
	global_load_dwordx4 v[108:111], v130, s[40:41] nt
	global_load_dwordx4 v[104:107], v130, s[40:41] offset:64 nt
	global_load_dwordx4 v[100:103], v130, s[40:41] offset:512 nt
	global_load_dwordx4 v[96:99], v130, s[40:41] offset:576 nt
	global_load_dwordx4 v[92:95], v128, s[40:41] nt
	global_load_dwordx4 v[88:91], v128, s[40:41] offset:64 nt
	global_load_dwordx4 v[84:87], v128, s[40:41] offset:512 nt
	global_load_dwordx4 v[80:83], v128, s[40:41] offset:576 nt
	global_load_dwordx4 v[76:79], v112, s[40:41] nt
	global_load_dwordx4 v[72:75], v112, s[40:41] offset:64 nt
	global_load_dwordx4 v[68:71], v112, s[40:41] offset:512 nt
	s_waitcnt lgkmcnt(0)
	global_load_dwordx4 v[64:67], v112, s[40:41] offset:576 nt
	s_waitcnt vmcnt(15)
	v_pk_add_f32 v[62:63], v[62:63], v[222:223]
	v_pk_add_f32 v[60:61], v[60:61], v[220:221]
	v_mul_f32_e32 v129, v63, v63
	v_mul_f32_e32 v113, v61, v61
	v_fmac_f32_e32 v113, v60, v60
	v_fmac_f32_e32 v129, v62, v62
	s_waitcnt vmcnt(14)
	v_pk_add_f32 v[58:59], v[58:59], v[226:227]
	v_pk_add_f32 v[56:57], v[56:57], v[224:225]
	v_add_f32_e32 v113, v113, v129
	v_mul_f32_e32 v129, v57, v57
	v_mul_f32_e32 v131, v59, v59
	v_fmac_f32_e32 v129, v56, v56
	v_fmac_f32_e32 v131, v58, v58
	v_add_f32_e32 v129, v129, v131
	s_waitcnt vmcnt(13)
	v_pk_add_f32 v[54:55], v[54:55], v[230:231]
	v_pk_add_f32 v[52:53], v[52:53], v[228:229]
	v_add_f32_e32 v113, v113, v129
	v_mul_f32_e32 v129, v53, v53
	v_mul_f32_e32 v131, v55, v55
	v_fmac_f32_e32 v129, v52, v52
	v_fmac_f32_e32 v131, v54, v54
	v_add_f32_e32 v129, v129, v131
	s_waitcnt vmcnt(12)
	v_pk_add_f32 v[46:47], v[46:47], v[234:235]
	v_pk_add_f32 v[44:45], v[44:45], v[232:233]
	v_add_f32_e32 v113, v113, v129
	v_mul_f32_e32 v129, v45, v45
	v_mul_f32_e32 v131, v47, v47
	v_fmac_f32_e32 v129, v44, v44
	v_fmac_f32_e32 v131, v46, v46
	v_add_f32_e32 v129, v129, v131
	v_add_f32_e32 v113, v113, v129
	ds_bpermute_b32 v129, v191, v113
	s_waitcnt lgkmcnt(0)
	v_add_f32_e32 v113, v113, v129
	ds_bpermute_b32 v129, v193, v113
	s_and_saveexec_b64 s[34:35], s[0:1]
	s_cbranch_execz .LBB0_879
	s_waitcnt lgkmcnt(0)
	v_add_f32_e32 v113, v113, v129
	ds_write_b32 v219, v113 offset:2048
